# static s_setprio 1 for waves 4-7 during the attention phases (strategy 4: one static priority raise for the younger half)
# baseline (speedup 1.0000x reference)
; template <bool DOA, bool DOB>
; DI void p4_attention(const Args& a, LAS unsigned char* lds, int G) {
;     ...
;     if (DOA) for (int it = blockIdx.x; it < 256; it += G) {
;         const int xq = it & 7, yq = it >> 3, gq = yq >> 2, pq = yq & 3;
;         for (int j = 0; j < 4; ++j) {
;             const int combo = xq * 16 + 2 * gq + (j >> 1), b = combo >> 4, hd = combo & 15;
;             const bf16_t* Kg = KA + (size_t)(b * 16 + hd) * L * 192; const bf16_t* Vtg = VAT + (size_t)(b * 16 + hd) * 128 * L; const bf16_t* Qg = QA + (size_t)(b * 16 + hd) * L * 192;
;             const int qb = (j & 1) ? pq : 7 - pq;
;             int lo_ = lane; asm volatile("" : "+v"(lo_)); const int r = lo_ & 15, q = lo_ >> 4;
;             const int q0 = qb * 256, qi0 = q0 + 32 * wave + r, qi1 = qi0 + 16;
;             attn_core<192, false>(lds, Kg, Vtg, Qg + (size_t)qi0 * 192, Qg + (size_t)qi1 * 192, 4 * (qb + 1), qi0, qi1, q0 + 32 * wave + 31, nullptr, nullptr, nullptr, nullptr, 0, 0, o, lsum);
.LBB0_489:
	s_cmp_lt_i32 s56, 5
	s_cselect_b64 s[4:5], -1, 0
	s_and_b64 s[0:1], s[4:5], s[0:1]
	s_andn2_b64 vcc, exec, s[0:1]
	s_cbranch_vccnz .LBB0_507
	v_readfirstlane_b32 s0, v224
	s_cmpk_gt_i32 s2, 0xff
	s_waitcnt vmcnt(0)
	s_barrier
	s_cbranch_scc1 .LBB0_507
	v_readfirstlane_b32 s98, v224
	s_nop 3
	s_cmp_lt_u32 s98, 0x100
	s_cbranch_scc1 .Lprio_a_skip
	s_setprio 1
.Lprio_a_skip:
	s_add_u32 s24, s52, 0x6000000
	s_addc_u32 s25, s53, 0
	s_add_u32 s26, s52, 0xc000000
	s_addc_u32 s27, s53, 0
	s_add_u32 s30, s54, 0x9000000
	s_addc_u32 s31, s55, 0
	s_lshr_b32 s0, s0, 1
	v_mbcnt_lo_u32_b32 v194, -1, 0
	v_and_b32_e32 v191, 63, v224
	s_and_b32 s33, s0, 0x7fffffe0
	s_lshl_b32 s34, s2, 4
	s_lshl_b32 s35, s58, 4
	v_mov_b32_e32 v177, 0
	s_movk_i32 s36, 0x180
	s_movk_i32 s37, 0xc0
	s_movk_i32 s38, 0x88
	s_mov_b32 s39, 0x40000
	s_mov_b32 s5, 0
	v_mov_b32_e32 v192, 0xc0000
	s_mov_b32 s40, 0x6006000
	s_mov_b32 s41, 0xff800000
	s_mov_b64 s[6:7], 0x80
	s_mov_b64 s[10:11], 0x6000
	s_mov_b32 s42, 0x9000
	s_mov_b64 s[18:19], 0x11002f40
	s_mov_b32 s43, 0x11002000
	v_mov_b32_e32 v193, 0xff800000
	v_mbcnt_hi_u32_b32 v195, -1, v194
	s_mov_b32 s46, s2
	s_branch .LBB0_493

; template <bool DOA, bool DOB>
; DI void p4_attention(const Args& a, LAS unsigned char* lds, int G) {
;     ...
;     if (DOB) for (int it = blockIdx.x; it < 256; it += G) {
;         const int b = it & 7, jx = it >> 3;
;         const int* posb = a.pos + (size_t)b * L; const bf16_t* KIDXb = KIDX + (size_t)b * L * 64;
;         const bf16_t* Kg = KBn + (size_t)b * L * 128; const bf16_t* Vtg = VBT + (size_t)b * 128 * L;
;         for (int j = 0; j < 4; ++j) {
;             const int un = (j == 0) ? jx : (j == 1) ? 63 - jx : (j == 2) ? 64 + jx : 127 - jx;
;             int lo_ = lane; asm volatile("" : "+v"(lo_)); const int r = lo_ & 15, q = lo_ >> 4;
;             const int t0 = un * 16, t_0 = t0 + 2 * wave, t_1 = t_0 + 1;
;             indexer_unit(lds, smask + wave * 64, PROJ, KIDXb, posb, b * L + t_0, t_0, ((t0 + 15) >> 6) + 1, wave, lane);
;             __syncthreads();
;             const bf16_t* qp0 = QB + ((size_t)(b * L + t_0) * 16 + r) * 128; const bf16_t* qp1 = QB + ((size_t)(b * L + t_1) * 16 + r) * 128;
;             attn_core<128, true>(lds, Kg, Vtg, qp0, qp1, (t0 + 79) >> 6, 0, 0, 0, smask + (wave * 2 + 0) * 32, smask + (wave * 2 + 1) * 32, tb, posb, posb[t_0], posb[t_1], o, lsum);
.LBB0_507:
	s_cmp_lt_i32 s56, 6
	s_cselect_b64 s[0:1], -1, 0
	s_cmp_gt_i32 s57, 5
	s_cselect_b64 s[4:5], -1, 0
	s_and_b64 s[6:7], s[0:1], s[4:5]
	s_andn2_b64 vcc, exec, s[6:7]
	s_cbranch_vccnz .LBB0_683
	v_readfirstlane_b32 s98, v224
	s_nop 3
	s_cmp_lt_u32 s98, 0x100
	s_cbranch_scc1 .Lprio_b_skip
	s_setprio 1
.Lprio_b_skip:
	v_and_b32_e32 v0, 15, v224
	v_add_u32_e32 v1, 0x20000, v190
	v_lshrrev_b32_e32 v2, 4, v224
	s_mov_b64 s[0:1], 0
	s_movk_i32 s10, 0xff
	s_mov_b32 s11, 0x800000
	s_mov_b32 s18, 0x3f317217
	s_mov_b32 s19, 0x7f800000
	s_mov_b32 s20, 0x40051592
	s_movk_i32 s21, 0x60f
	v_mov_b32_e32 v3, 0x41b17218
	v_mov_b32_e32 v4, v224
	s_branch .LBB0_510
